# DIFF attention loop: O accumulators kept in place (v32-95) and QK result written directly by the last MFMA: 48 v_mov_b64 per 64-key iteration removed, on top of v2
# speedup vs baseline: 1.0110x; 1.0110x over previous
.LBB0_681:
	v_add3_u32 v1, s21, v209, v213
	ds_read_b128 v[6:9], v1
	ds_read_b128 v[10:13], v1 offset:32
	ds_read_b128 v[96:99], v1 offset:64
	ds_read_b128 v[2:5], v1 offset:96
	v_max_f32_e32 v1, v17, v17
	s_waitcnt lgkmcnt(3)
	v_mfma_f32_32x32x16_bf16 v[160:175], v[6:9], v[176:179], 0
	v_sub_f32_e32 v7, v16, v217
	v_exp_f32_e32 v7, v7
	v_sub_f32_e32 v9, v17, v217
	v_exp_f32_e32 v9, v9
	v_max_f32_e32 v14, v16, v16
	v_add_f32_e32 v8, 0, v7
	v_max_f32_e32 v1, v14, v1
	s_waitcnt lgkmcnt(2)
	v_mfma_f32_32x32x16_bf16 v[160:175], v[10:13], v[180:183], v[160:175]
	v_sub_f32_e32 v10, v18, v217
	v_exp_f32_e32 v11, v10
	v_sub_f32_e32 v10, v19, v217
	v_exp_f32_e32 v12, v10
	v_sub_f32_e32 v10, v20, v217
	v_exp_f32_e32 v13, v10
	v_sub_f32_e32 v10, v21, v217
	v_add_f32_e32 v8, v9, v8
	v_exp_f32_e32 v14, v10
	v_sub_f32_e32 v10, v22, v217
	v_add_f32_e32 v8, v11, v8
	v_exp_f32_e32 v15, v10
	v_sub_f32_e32 v10, v23, v217
	v_max3_f32 v1, v1, v18, v19
	v_add_f32_e32 v8, v12, v8
	v_exp_f32_e32 v16, v10
	v_sub_f32_e32 v10, v24, v217
	v_max3_f32 v1, v1, v20, v21
	v_add_f32_e32 v8, v13, v8
	v_exp_f32_e32 v17, v10
	v_sub_f32_e32 v10, v25, v217
	v_max3_f32 v1, v1, v22, v23
	v_add_f32_e32 v8, v14, v8
	v_exp_f32_e32 v18, v10
	v_sub_f32_e32 v10, v26, v217
	v_max3_f32 v1, v1, v24, v25
	v_add_f32_e32 v8, v15, v8
	v_exp_f32_e32 v19, v10
	v_sub_f32_e32 v10, v27, v217
	v_max3_f32 v1, v1, v26, v27
	v_add_f32_e32 v8, v16, v8
	v_exp_f32_e32 v20, v10
	v_sub_f32_e32 v10, v28, v217
	v_max3_f32 v1, v1, v28, v29
	v_add_f32_e32 v8, v17, v8
	v_exp_f32_e32 v21, v10
	v_sub_f32_e32 v10, v29, v217
	v_max3_f32 v1, v1, v30, v31
	v_add_f32_e32 v8, v18, v8
	v_exp_f32_e32 v22, v10
	v_sub_f32_e32 v10, v30, v217
	ds_bpermute_b32 v6, v247, v1
	v_add_f32_e32 v8, v19, v8
	v_exp_f32_e32 v23, v10
	v_sub_f32_e32 v10, v31, v217
	v_add_f32_e32 v8, v20, v8
	v_exp_f32_e32 v24, v10
	v_add_f32_e32 v8, v21, v8
	v_add_f32_e32 v8, v22, v8
	v_add_f32_e32 v8, v23, v8
	s_mulk_i32 s31, 0x4800
	v_add_f32_e32 v8, v24, v8
	s_waitcnt lgkmcnt(0)
	v_max_f32_e32 v6, v6, v6
	v_max_f32_e32 v210, v1, v6
	v_add_f32_e32 v1, v216, v8
	v_cvt_pk_bf16_f32 v8, v21, v22
	v_add_u32_e32 v22, s31, v223
	v_cvt_pk_bf16_f32 v10, v7, v9
	v_cvt_pk_bf16_f32 v11, v11, v12
	v_cvt_pk_bf16_f32 v12, v13, v14
	v_cvt_pk_bf16_f32 v13, v15, v16
	v_cvt_pk_bf16_f32 v6, v17, v18
	v_cvt_pk_bf16_f32 v7, v19, v20
	ds_read_b128 v[14:17], v22 offset:18496
	ds_read_b128 v[18:21], v22 offset:18528
	v_mfma_f32_32x32x16_bf16 v[160:175], v[96:99], v[184:187], v[160:175]
	v_cvt_pk_bf16_f32 v9, v23, v24
	s_waitcnt lgkmcnt(1)
	v_mfma_f32_32x32x16_bf16 v[32:47], v[14:17], v[10:13], v[32:47]
	ds_read_b128 v[14:17], v22 offset:23104
	s_waitcnt lgkmcnt(0)
	v_mfma_f32_32x32x16_bf16 v[48:63], v[14:17], v[10:13], v[48:63]
	ds_read_b128 v[14:17], v22 offset:23136
	s_waitcnt lgkmcnt(0)
	v_mfma_f32_32x32x16_bf16 v[48:63], v[14:17], v[6:9], v[48:63]
	ds_read_b128 v[14:17], v22 offset:27712
	s_waitcnt lgkmcnt(0)
	v_mfma_f32_32x32x16_bf16 v[64:79], v[14:17], v[10:13], v[64:79]
	ds_read_b128 v[14:17], v22 offset:27744
	s_waitcnt lgkmcnt(0)
	v_mfma_f32_32x32x16_bf16 v[64:79], v[14:17], v[6:9], v[64:79]
	ds_read_b128 v[14:17], v22 offset:32320
	s_waitcnt lgkmcnt(0)
	v_mfma_f32_32x32x16_bf16 v[80:95], v[14:17], v[10:13], v[80:95]
	ds_read_b128 v[10:13], v22 offset:32352
	v_mfma_f32_32x32x16_bf16 v[32:47], v[18:21], v[6:9], v[32:47]
	s_waitcnt lgkmcnt(0)
	v_mfma_f32_32x32x16_bf16 v[80:95], v[10:13], v[6:9], v[80:95]
	v_mfma_f32_32x32x16_bf16 v[16:31], v[2:5], v[188:191], v[160:175]
	v_sub_f32_e32 v2, v210, v217
	v_cmp_lt_f32_e32 vcc, s2, v2
	s_cbranch_vccz .LBB0_698
	v_max_f32_e32 v2, v2, v2
	v_max_f32_e32 v3, 0, v2
	v_exp_f32_e64 v2, -v3
	v_add_f32_e32 v6, v217, v3
	v_mul_f32_e32 v1, v2, v1
	s_nop 3
	v_pk_mul_f32 v[46:47], v[46:47], v[2:3] op_sel_hi:[1,0]
	v_pk_mul_f32 v[44:45], v[44:45], v[2:3] op_sel_hi:[1,0]
	v_pk_mul_f32 v[42:43], v[42:43], v[2:3] op_sel_hi:[1,0]
	v_pk_mul_f32 v[40:41], v[40:41], v[2:3] op_sel_hi:[1,0]
	v_pk_mul_f32 v[38:39], v[38:39], v[2:3] op_sel_hi:[1,0]
	v_pk_mul_f32 v[36:37], v[36:37], v[2:3] op_sel_hi:[1,0]
	v_pk_mul_f32 v[34:35], v[34:35], v[2:3] op_sel_hi:[1,0]
	v_pk_mul_f32 v[32:33], v[32:33], v[2:3] op_sel_hi:[1,0]
	v_pk_mul_f32 v[62:63], v[62:63], v[2:3] op_sel_hi:[1,0]
	v_pk_mul_f32 v[60:61], v[60:61], v[2:3] op_sel_hi:[1,0]
	v_pk_mul_f32 v[58:59], v[58:59], v[2:3] op_sel_hi:[1,0]
	v_pk_mul_f32 v[56:57], v[56:57], v[2:3] op_sel_hi:[1,0]
	v_pk_mul_f32 v[54:55], v[54:55], v[2:3] op_sel_hi:[1,0]
	v_pk_mul_f32 v[52:53], v[52:53], v[2:3] op_sel_hi:[1,0]
	v_pk_mul_f32 v[50:51], v[50:51], v[2:3] op_sel_hi:[1,0]
	v_pk_mul_f32 v[48:49], v[48:49], v[2:3] op_sel_hi:[1,0]
	v_pk_mul_f32 v[78:79], v[2:3], v[78:79] op_sel_hi:[0,1]
	v_pk_mul_f32 v[76:77], v[2:3], v[76:77] op_sel_hi:[0,1]
	v_pk_mul_f32 v[74:75], v[2:3], v[74:75] op_sel_hi:[0,1]
	v_pk_mul_f32 v[72:73], v[2:3], v[72:73] op_sel_hi:[0,1]
	v_pk_mul_f32 v[70:71], v[2:3], v[70:71] op_sel_hi:[0,1]
	v_pk_mul_f32 v[68:69], v[2:3], v[68:69] op_sel_hi:[0,1]
	v_pk_mul_f32 v[66:67], v[2:3], v[66:67] op_sel_hi:[0,1]
	v_pk_mul_f32 v[64:65], v[2:3], v[64:65] op_sel_hi:[0,1]
	v_pk_mul_f32 v[94:95], v[2:3], v[94:95] op_sel_hi:[0,1]
	v_pk_mul_f32 v[92:93], v[2:3], v[92:93] op_sel_hi:[0,1]
	v_pk_mul_f32 v[90:91], v[2:3], v[90:91] op_sel_hi:[0,1]
	v_pk_mul_f32 v[88:89], v[2:3], v[88:89] op_sel_hi:[0,1]
	v_pk_mul_f32 v[86:87], v[2:3], v[86:87] op_sel_hi:[0,1]
	v_pk_mul_f32 v[84:85], v[2:3], v[84:85] op_sel_hi:[0,1]
	v_pk_mul_f32 v[82:83], v[2:3], v[82:83] op_sel_hi:[0,1]
	v_pk_mul_f32 v[80:81], v[2:3], v[80:81] op_sel_hi:[0,1]
	s_cbranch_execz .LBB0_685
	s_branch .LBB0_686

.LBB0_684:
	v_mov_b32_e32 v6, v217
	v_mov_b32_e32 v1, v216
	s_cbranch_execnz .LBB0_686
.LBB0_685:
	v_add3_u32 v1, s21, v209, v213
	ds_read_b128 v[2:5], v1
	ds_read_b128 v[6:9], v1 offset:32
	s_nop 0
	s_nop 0
	s_nop 0
	s_waitcnt lgkmcnt(1)
	v_mfma_f32_32x32x16_bf16 v[16:31], v[2:5], v[176:179], 0
	s_nop 0
	s_nop 0
	s_nop 0
	s_nop 0
	s_nop 0
	s_nop 0
	s_nop 0
	s_waitcnt lgkmcnt(0)
	v_mfma_f32_32x32x16_bf16 v[16:31], v[6:9], v[180:183], v[16:31]
	ds_read_b128 v[2:5], v1 offset:64
	ds_read_b128 v[6:9], v1 offset:96
	s_nop 0
	s_nop 0
	s_nop 0
	s_nop 0
	s_nop 0
	s_nop 0
	s_waitcnt lgkmcnt(1)
	v_mfma_f32_32x32x16_bf16 v[16:31], v[2:5], v[184:187], v[16:31]
	s_nop 0
	s_nop 0
	s_nop 0
	s_nop 0
	s_nop 0
	s_nop 0
	s_nop 0
	s_waitcnt lgkmcnt(0)
	v_mfma_f32_32x32x16_bf16 v[16:31], v[6:9], v[188:191], v[16:31]
	s_nop 0
	s_nop 0
	s_nop 0
	s_nop 0
	s_nop 0
	s_nop 0
	s_nop 0
	s_nop 0
	s_nop 0
	v_mov_b32_e32 v1, v216
	v_mov_b32_e32 v6, v217
.LBB0_686:
	s_cmp_ge_i32 s30, s6
	s_cbranch_scc1 .LBB0_702
	s_cmp_gt_i32 s15, s7
	s_cbranch_scc1 .LBB0_702
	s_cmp_lt_u32 s30, 32
	s_cselect_b64 s[30:31], -1, 0
	s_sub_i32 s33, s15, 64
	s_and_b64 s[30:31], s[30:31], exec
	s_cselect_b32 s33, s15, s33
	s_cselect_b32 s31, s41, s43
	s_cselect_b32 s30, s40, s42
	s_lshr_b64 s[30:31], s[30:31], s33
	s_and_b32 s30, s30, 1
	s_mov_b32 s31, s77
	s_cmp_eq_u64 s[30:31], 0
	s_cbranch_scc1 .LBB0_690
	v_lshl_add_u32 v7, s19, 8, v249
	ds_read_b128 v[2:5], v7
	ds_read_b128 v[8:11], v7 offset:32
	s_waitcnt lgkmcnt(1)
	v_sub_u32_e32 v2, v244, v2
	v_med3_i32 v2, v2, 0, v248
	v_lshl_add_u32 v12, v2, 2, s3
	v_sub_u32_e32 v2, v244, v4
	v_med3_i32 v2, v2, 0, v248
	v_lshl_add_u32 v14, v2, 2, s3
	v_sub_u32_e32 v2, v244, v5
	v_med3_i32 v2, v2, 0, v248
	v_lshl_add_u32 v15, v2, 2, s3
	s_waitcnt lgkmcnt(0)
	v_sub_u32_e32 v2, v244, v8
	v_med3_i32 v2, v2, 0, v248
	v_lshl_add_u32 v96, v2, 2, s3
	v_sub_u32_e32 v2, v244, v9
	v_med3_i32 v2, v2, 0, v248
	v_sub_u32_e32 v3, v244, v3
	v_lshl_add_u32 v97, v2, 2, s3
	v_sub_u32_e32 v2, v244, v10
	v_sub_u32_e32 v8, v244, v11
	v_med3_i32 v3, v3, 0, v248
	v_med3_i32 v2, v2, 0, v248
	v_med3_i32 v8, v8, 0, v248
	v_lshl_add_u32 v13, v3, 2, s3
	v_lshl_add_u32 v98, v2, 2, s3
	ds_read_b128 v[2:5], v7 offset:64
	v_lshl_add_u32 v99, v8, 2, s3
	ds_read_b128 v[8:11], v7 offset:96
	s_waitcnt lgkmcnt(1)
	v_sub_u32_e32 v2, v244, v2
	v_sub_u32_e32 v3, v244, v3
	s_waitcnt lgkmcnt(0)
	v_sub_u32_e32 v7, v244, v8
	v_sub_u32_e32 v8, v244, v9
	v_med3_i32 v8, v8, 0, v248
	v_lshl_add_u32 v9, v8, 2, s3
	v_sub_u32_e32 v8, v244, v10
	v_med3_i32 v8, v8, 0, v248
	v_sub_u32_e32 v4, v244, v4
	v_sub_u32_e32 v5, v244, v5
	v_lshl_add_u32 v10, v8, 2, s3
	v_sub_u32_e32 v8, v244, v11
	v_med3_i32 v2, v2, 0, v248
	v_med3_i32 v3, v3, 0, v248
	v_med3_i32 v4, v4, 0, v248
	v_med3_i32 v5, v5, 0, v248
	v_med3_i32 v8, v8, 0, v248
	v_lshl_add_u32 v2, v2, 2, s3
	v_lshl_add_u32 v3, v3, 2, s3
	v_lshl_add_u32 v4, v4, 2, s3
	v_lshl_add_u32 v5, v5, 2, s3
	v_med3_i32 v7, v7, 0, v248
	v_lshl_add_u32 v11, v8, 2, s3
	v_lshl_add_u32 v7, v7, 2, s3
	ds_read_b32 v2, v2
	ds_read_b32 v3, v3
	ds_read_b32 v4, v4
	ds_read_b32 v5, v5
	ds_read_b32 v8, v7
	ds_read_b32 v9, v9
	ds_read_b32 v10, v10
	ds_read_b32 v11, v11
	ds_read_b32 v12, v12
	ds_read_b32 v13, v13
	ds_read_b32 v14, v14
	ds_read_b32 v15, v15
	ds_read_b32 v96, v96
	ds_read_b32 v97, v97
	ds_read_b32 v98, v98
	ds_read_b32 v99, v99
	s_waitcnt lgkmcnt(8)
	v_pk_add_f32 v[30:31], v[30:31], v[10:11]
	v_pk_add_f32 v[28:29], v[28:29], v[8:9]
	v_pk_add_f32 v[26:27], v[26:27], v[4:5]
	v_pk_add_f32 v[24:25], v[24:25], v[2:3]
	s_waitcnt lgkmcnt(0)
	v_pk_add_f32 v[22:23], v[22:23], v[98:99]
	v_pk_add_f32 v[20:21], v[20:21], v[96:97]
	v_pk_add_f32 v[18:19], v[18:19], v[14:15]
	v_pk_add_f32 v[16:17], v[16:17], v[12:13]

.LBB0_694:
	v_add3_u32 v119, s21, v209, v213
	ds_read_b128 v[2:5], v119 offset:4608
	ds_read_b128 v[10:13], v119 offset:4640
	s_mul_i32 s21, s19, 0x4800
	v_add_u32_e32 v132, s21, v223
	v_sub_f32_e32 v113, v22, v6
	v_sub_f32_e32 v14, v19, v6
	v_sub_f32_e32 v114, v23, v6
	v_sub_f32_e32 v15, v20, v6
	v_sub_f32_e32 v115, v24, v6
	s_waitcnt lgkmcnt(1)
	v_mfma_f32_32x32x16_bf16 v[96:111], v[2:5], v[176:179], 0
	ds_read_b128 v[2:5], v119 offset:4672
	ds_read_b128 v[124:127], v132 offset:18464
	v_sub_f32_e32 v7, v16, v6
	v_sub_f32_e32 v8, v17, v6
	v_sub_f32_e32 v9, v18, v6
	v_sub_f32_e32 v112, v21, v6
	v_exp_f32_e32 v7, v7
	s_waitcnt lgkmcnt(2)
	v_mfma_f32_32x32x16_bf16 v[96:111], v[10:13], v[180:183], v[96:111]
	v_exp_f32_e32 v13, v113
	v_exp_f32_e32 v10, v14
	v_exp_f32_e32 v14, v114
	v_exp_f32_e32 v11, v15
	v_exp_f32_e32 v15, v115
	v_exp_f32_e32 v8, v8
	v_exp_f32_e32 v9, v9
	s_waitcnt lgkmcnt(1)
	v_mfma_f32_32x32x16_bf16 v[96:111], v[2:5], v[184:187], v[96:111]
	v_sub_f32_e32 v2, v26, v6
	v_exp_f32_e32 v113, v2
	v_sub_f32_e32 v2, v27, v6
	v_exp_f32_e32 v114, v2
	v_sub_f32_e32 v2, v28, v6
	v_exp_f32_e32 v115, v2
	ds_read_b128 v[2:5], v132 offset:18432
	ds_read_b128 v[128:131], v132 offset:32256
	v_exp_f32_e32 v12, v112
	v_cvt_pk_bf16_f32 v120, v7, v8
	v_cvt_pk_bf16_f32 v121, v9, v10
	v_cvt_pk_bf16_f32 v123, v13, v14
	v_cvt_pk_bf16_f32 v122, v11, v12
	v_sub_f32_e32 v116, v25, v6
	v_exp_f32_e32 v112, v116
	s_waitcnt lgkmcnt(1)
	v_mfma_f32_32x32x16_bf16 v[32:47], v[2:5], v[120:123], v[32:47]
	v_sub_f32_e32 v116, v29, v6
	v_sub_f32_e32 v117, v30, v6
	v_sub_f32_e32 v2, v31, v6
	v_exp_f32_e32 v116, v116
	v_exp_f32_e32 v117, v117
	v_exp_f32_e32 v118, v2
	v_cvt_pk_bf16_f32 v2, v15, v112
	v_cvt_pk_bf16_f32 v3, v113, v114
	v_cvt_pk_bf16_f32 v4, v115, v116
	v_cvt_pk_bf16_f32 v5, v117, v118
	v_max_f32_e32 v17, v17, v17
	v_max_f32_e32 v16, v16, v16
	v_mfma_f32_32x32x16_bf16 v[32:47], v[124:127], v[2:5], v[32:47]
	ds_read_b128 v[124:127], v132 offset:23040
	v_max_f32_e32 v16, v16, v17
	v_max3_f32 v16, v16, v18, v19
	v_max3_f32 v16, v16, v20, v21
	v_max3_f32 v16, v16, v22, v23
	v_max3_f32 v20, v16, v24, v25
	ds_read_b128 v[16:19], v132 offset:32288
	s_waitcnt lgkmcnt(1)
	v_mfma_f32_32x32x16_bf16 v[48:63], v[124:127], v[120:123], v[48:63]
	ds_read_b128 v[124:127], v132 offset:23072
	v_max3_f32 v20, v20, v26, v27
	v_max3_f32 v20, v20, v28, v29
	v_max3_f32 v20, v20, v30, v31
	ds_bpermute_b32 v21, v247, v20
	s_andn2_b64 vcc, exec, s[92:93]
	s_waitcnt lgkmcnt(1)
	v_mfma_f32_32x32x16_bf16 v[48:63], v[124:127], v[2:5], v[48:63]
	ds_read_b128 v[124:127], v132 offset:27648
	s_waitcnt lgkmcnt(0)
	v_mfma_f32_32x32x16_bf16 v[64:79], v[124:127], v[120:123], v[64:79]
	ds_read_b128 v[124:127], v132 offset:27680
	v_mfma_f32_32x32x16_bf16 v[80:95], v[128:131], v[120:123], v[80:95]
	ds_read_b128 v[120:123], v119 offset:4704
	s_waitcnt lgkmcnt(1)
	v_mfma_f32_32x32x16_bf16 v[64:79], v[124:127], v[2:5], v[64:79]
	v_mfma_f32_32x32x16_bf16 v[80:95], v[16:19], v[2:5], v[80:95]
	v_max_f32_e32 v2, v21, v21
	v_max_f32_e32 v2, v20, v2
	v_sub_f32_e32 v2, v2, v6
	s_waitcnt lgkmcnt(0)
	v_mfma_f32_32x32x16_bf16 v[16:31], v[120:123], v[188:191], v[96:111]
	s_cbranch_vccnz .LBB0_697
	v_cmp_lt_f32_e32 vcc, s2, v2
	s_cbranch_vccz .LBB0_699
	v_max_f32_e32 v2, v2, v2
	v_max_f32_e32 v2, 0, v2

.LBB0_700:
	v_add_f32_e32 v3, 0, v7
	v_add_f32_e32 v3, v8, v3
	v_add_f32_e32 v3, v9, v3
	v_add_f32_e32 v3, v10, v3
	v_add_f32_e32 v3, v11, v3
	v_add_f32_e32 v3, v12, v3
	v_add_f32_e32 v3, v13, v3
	v_add_f32_e32 v3, v14, v3
	v_add_f32_e32 v3, v15, v3
	v_add_f32_e32 v3, v112, v3
	v_add_f32_e32 v3, v113, v3
	v_add_f32_e32 v3, v114, v3
	v_add_f32_e32 v3, v115, v3
	v_add_f32_e32 v3, v116, v3
	v_add_f32_e32 v3, v117, v3
	v_add_f32_e32 v3, v118, v3
	v_add_f32_e32 v1, v1, v3
	s_and_b64 vcc, exec, s[48:49]
	s_cbranch_vccz .LBB0_702
	v_exp_f32_e64 v4, -v2
	v_add_f32_e32 v6, v6, v2
	v_mul_f32_e32 v1, v1, v4
	v_pk_mul_f32 v[46:47], v[46:47], v[4:5] op_sel_hi:[1,0]
	v_pk_mul_f32 v[44:45], v[44:45], v[4:5] op_sel_hi:[1,0]
	v_pk_mul_f32 v[42:43], v[42:43], v[4:5] op_sel_hi:[1,0]
	v_pk_mul_f32 v[40:41], v[40:41], v[4:5] op_sel_hi:[1,0]
	v_pk_mul_f32 v[38:39], v[38:39], v[4:5] op_sel_hi:[1,0]
	v_pk_mul_f32 v[36:37], v[36:37], v[4:5] op_sel_hi:[1,0]
	v_pk_mul_f32 v[34:35], v[34:35], v[4:5] op_sel_hi:[1,0]
	v_pk_mul_f32 v[32:33], v[32:33], v[4:5] op_sel_hi:[1,0]
	v_pk_mul_f32 v[62:63], v[62:63], v[4:5] op_sel_hi:[1,0]
	v_pk_mul_f32 v[60:61], v[60:61], v[4:5] op_sel_hi:[1,0]
	v_pk_mul_f32 v[58:59], v[58:59], v[4:5] op_sel_hi:[1,0]
	v_pk_mul_f32 v[56:57], v[56:57], v[4:5] op_sel_hi:[1,0]
	v_pk_mul_f32 v[54:55], v[54:55], v[4:5] op_sel_hi:[1,0]
	v_pk_mul_f32 v[52:53], v[52:53], v[4:5] op_sel_hi:[1,0]
	v_pk_mul_f32 v[50:51], v[50:51], v[4:5] op_sel_hi:[1,0]
	v_pk_mul_f32 v[48:49], v[48:49], v[4:5] op_sel_hi:[1,0]
	v_pk_mul_f32 v[78:79], v[78:79], v[4:5] op_sel_hi:[1,0]
	v_pk_mul_f32 v[76:77], v[76:77], v[4:5] op_sel_hi:[1,0]
	v_pk_mul_f32 v[74:75], v[74:75], v[4:5] op_sel_hi:[1,0]
	v_pk_mul_f32 v[72:73], v[72:73], v[4:5] op_sel_hi:[1,0]
	v_pk_mul_f32 v[70:71], v[70:71], v[4:5] op_sel_hi:[1,0]
	v_pk_mul_f32 v[68:69], v[68:69], v[4:5] op_sel_hi:[1,0]
	v_pk_mul_f32 v[66:67], v[66:67], v[4:5] op_sel_hi:[1,0]
	v_pk_mul_f32 v[64:65], v[64:65], v[4:5] op_sel_hi:[1,0]
	v_pk_mul_f32 v[94:95], v[94:95], v[4:5] op_sel_hi:[1,0]
	v_pk_mul_f32 v[92:93], v[92:93], v[4:5] op_sel_hi:[1,0]
	v_pk_mul_f32 v[90:91], v[90:91], v[4:5] op_sel_hi:[1,0]
	v_pk_mul_f32 v[88:89], v[88:89], v[4:5] op_sel_hi:[1,0]
	v_pk_mul_f32 v[86:87], v[86:87], v[4:5] op_sel_hi:[1,0]
	v_pk_mul_f32 v[84:85], v[84:85], v[4:5] op_sel_hi:[1,0]
	v_pk_mul_f32 v[82:83], v[82:83], v[4:5] op_sel_hi:[1,0]
	v_pk_mul_f32 v[80:81], v[80:81], v[4:5] op_sel_hi:[1,0]
.LBB0_702:
	v_mov_b32_e32 v216, v1
	v_mov_b32_e32 v217, v6
	s_add_i32 s21, s18, 1
	s_waitcnt lgkmcnt(0)
	s_barrier
	s_cmp_lg_u32 s18, 2
	s_cselect_b32 s30, s21, 0
	s_add_i32 s15, s15, 2
	s_add_i32 s76, s76, 64
	s_cmp_eq_u32 s14, s20
	s_cbranch_scc1 .LBB0_705
	s_mov_b32 s21, s18
	s_mov_b32 s31, s19
	s_mov_b32 s18, s30
	s_mov_b32 s30, s20
	s_add_i32 s20, s30, 1
	s_mov_b32 s19, s21
	s_cmp_ge_i32 s20, s6
	s_cbranch_scc0 .LBB0_666
	s_branch .LBB0_669
